# N<=512 top-k variant gets the sorted-block counting pass and scalar loop control too
# speedup vs baseline: 1.0075x; 1.0004x over previous
.LBB0_1241:
	ds_read_b32 v10, v28
	v_or_b32_e32 v2, 64, v16
	v_cmp_gt_u32_e32 vcc, s72, v2
	v_mov_b32_e32 v8, 0
	v_mov_b32_e32 v9, 0
	s_and_saveexec_b64 s[0:1], vcc
	ds_read_b32 v9, v28 offset:256
	s_or_b64 exec, exec, s[0:1]
	v_or_b32_e32 v2, 0x80, v16
	v_cmp_gt_u32_e32 vcc, s72, v2
	s_and_saveexec_b64 s[0:1], vcc
	ds_read_b32 v8, v28 offset:512
	s_or_b64 exec, exec, s[0:1]
	v_or_b32_e32 v2, 0xc0, v16
	v_cmp_gt_u32_e32 vcc, s72, v2
	v_mov_b32_e32 v6, 0
	v_mov_b32_e32 v7, 0
	s_and_saveexec_b64 s[0:1], vcc
	ds_read_b32 v7, v28 offset:768
	s_or_b64 exec, exec, s[0:1]
	v_or_b32_e32 v2, 0x100, v16
	v_cmp_gt_u32_e32 vcc, s72, v2
	s_and_saveexec_b64 s[0:1], vcc
	ds_read_b32 v6, v28 offset:1024
	s_or_b64 exec, exec, s[0:1]
	v_or_b32_e32 v2, 0x140, v16
	v_cmp_gt_u32_e32 vcc, s72, v2
	v_mov_b32_e32 v3, 0
	v_mov_b32_e32 v5, 0
	s_and_saveexec_b64 s[0:1], vcc
	ds_read_b32 v5, v28 offset:1280
	s_or_b64 exec, exec, s[0:1]
	v_or_b32_e32 v2, 0x180, v16
	v_cmp_gt_u32_e32 vcc, s72, v2
	s_and_saveexec_b64 s[0:1], vcc
	ds_read_b32 v3, v28 offset:1536
	s_or_b64 exec, exec, s[0:1]
	v_or_b32_e32 v2, 0x1c0, v16
	v_cmp_gt_u32_e32 vcc, s72, v2
	v_mov_b32_e32 v2, 0
	s_and_saveexec_b64 s[0:1], vcc
	ds_read_b32 v2, v28 offset:1792
	s_or_b64 exec, exec, s[0:1]
	s_cmpk_gt_u32 s71, 0xdff
	v_mov_b32_e32 v4, 1
	s_cbranch_scc1 .LBB0_1258
	v_mov_b32_e32 v11, 31
	v_mov_b32_e32 v4, 0
	s_waitcnt lgkmcnt(0)
	s_waitcnt vmcnt(0)
	v_max_u32_e32 v142, v10, v6
	v_min_u32_e32 v143, v10, v6
	v_max_u32_e32 v144, v9, v5
	v_min_u32_e32 v145, v9, v5
	v_max_u32_e32 v146, v8, v3
	v_min_u32_e32 v147, v8, v3
	v_max_u32_e32 v148, v7, v2
	v_min_u32_e32 v149, v7, v2
	v_max_u32_e32 v150, v142, v146
	v_min_u32_e32 v151, v142, v146
	v_max_u32_e32 v146, v144, v148
	v_min_u32_e32 v142, v144, v148
	v_max_u32_e32 v148, v143, v147
	v_min_u32_e32 v144, v143, v147
	v_max_u32_e32 v147, v145, v149
	v_min_u32_e32 v143, v145, v149
	v_max_u32_e32 v149, v151, v148
	v_min_u32_e32 v145, v151, v148
	v_max_u32_e32 v148, v142, v147
	v_min_u32_e32 v151, v142, v147
	v_max_u32_e32 v147, v150, v146
	v_min_u32_e32 v142, v150, v146
	v_max_u32_e32 v146, v149, v148
	v_min_u32_e32 v150, v149, v148
	v_max_u32_e32 v148, v145, v151
	v_min_u32_e32 v149, v145, v151
	v_max_u32_e32 v151, v144, v143
	v_min_u32_e32 v145, v144, v143
	v_max_u32_e32 v143, v142, v148
	v_min_u32_e32 v144, v142, v148
	v_max_u32_e32 v148, v150, v151
	v_min_u32_e32 v142, v150, v151
	v_max_u32_e32 v151, v143, v146
	v_min_u32_e32 v150, v143, v146
	v_max_u32_e32 v146, v148, v144
	v_min_u32_e32 v143, v148, v144
	v_max_u32_e32 v144, v149, v142
	v_min_u32_e32 v148, v149, v142
	s_mov_b32 s12, 0
	s_mov_b32 s13, 31
.LBB0_1257:
	s_lshl_b32 s14, 1, s13
	s_or_b32 s14, s14, s12
	v_cmp_ge_u32_e64 s[4:5], v146, s14
	v_cmp_ge_u32_e64 s[10:11], v145, s14
	s_nop 0
	v_cndmask_b32_e64 v134, v151, v144, s[4:5]
	v_cmp_ge_u32_e64 s[6:7], v134, s14
	s_nop 1
	v_cndmask_b32_e64 v134, v147, v150, s[6:7]
	v_cndmask_b32_e64 v135, v143, v148, s[6:7]
	v_cndmask_b32_e64 v134, v134, v135, s[4:5]
	v_cmp_ge_u32_e64 s[8:9], v134, s14
	s_bcnt1_i32_b64 s1, s[4:5]
	s_mov_b32 s0, s1
	s_bcnt1_i32_b64 s1, s[6:7]
	s_lshl1_add_u32 s0, s0, s1
	s_bcnt1_i32_b64 s1, s[8:9]
	s_lshl1_add_u32 s0, s0, s1
	s_bcnt1_i32_b64 s1, s[10:11]
	s_add_i32 s0, s0, s1
	s_mov_b32 s2, s0
	s_cmpk_ge_u32 s2, 0x100
	s_cselect_b32 s12, s14, s12
	s_cmpk_eq_u32 s2, 0x100
	s_cbranch_scc1 .Lbt_exit_8
	s_sub_u32 s13, s13, 1
	s_cbranch_scc0 .LBB0_1257
.Lbt_exit_8:
	v_mov_b32_e32 v4, s12
	s_cmpk_eq_i32 s2, 0x100
	s_cbranch_scc1 .Lselfast_8
